# nt cache policy on the f32 output stores of the last down-projection epilogue
# baseline (speedup 1.0000x reference)
; #define EPIRES_LOAD(slot, q) do { _Pragma("unroll") for (int mm = 0; mm < 2; ++mm) { const size_t off_ = (size_t)(row0 + ((q) >> 1) * HALF + (2 * ((q) & 1) + mm) * 16) * 1024 + col0; \
;             _Pragma("unroll") for (int bj = 0; bj < 2; ++bj) { \
;                 pre[slot][mm][bj] = *(const u32x4*)(res16 + off_ + bj * HALF); } } } while (0)
;     __device__ __forceinline__ void operator()(const f32x4 (&acc)[2][2][4][2], const Unit& u, int wr, int wc, int fr, int fq, PG8_LAS unsigned char* lds, int& rs_pm, int& rs_tog) const {
;         const int row0 = u.pm * BM + wr * 64 + fr, col0 = u.pn * BM + wc * 32 + 8 * fq;
;         u32x4 pre[4][2][2];
;     ...
;         EPIRES_LOAD(0, 0); EPIRES_LOAD(1, 1); EPIRES_LOAD(2, 2); EPIRES_LOAD(3, 3);
; #pragma unroll
;         for (int q = 0; q < 4; ++q) {
;             const int ai = q >> 1, slot = q;
; #pragma unroll
;             for (int mm = 0; mm < 2; ++mm) {
;                 const int m = 2 * (q & 1) + mm; const size_t off = (size_t)(row0 + ai * HALF + m * 16) * 1024 + col0; float qs = 0.f;
; #pragma unroll
;                 for (int bj = 0; bj < 2; ++bj) {
;                     const u32x4 w_ = pre[slot][mm][bj];
;                     const f32x4 r0 = (f32x4){__uint_as_float(w_.x << 16), __uint_as_float(w_.x & 0xffff0000u), __uint_as_float(w_.y << 16), __uint_as_float(w_.y & 0xffff0000u)};
;                     const f32x4 r1 = (f32x4){__uint_as_float(w_.z << 16), __uint_as_float(w_.z & 0xffff0000u), __uint_as_float(w_.w << 16), __uint_as_float(w_.w & 0xffff0000u)};
;                     const f32x4 v0 = acc[ai][bj][m][0] + r0, v1 = acc[ai][bj][m][1] + r1;
;                     if (out32) { *(f32x4*)(out32 + off + bj * HALF) = v0; *(f32x4*)(out32 + off + bj * HALF + 4) = v1; }
.LBB0_277:
	v_lshl_add_u32 v210, s33, 8, v244
	v_lshl_or_b32 v212, s29, 8, v246
	v_ashrrev_i32_e32 v213, 31, v212
	v_ashrrev_i32_e32 v211, 31, v210
	v_lshl_add_u64 v[110:111], v[212:213], 1, s[70:71]
	v_lshlrev_b64 v[112:113], 11, v[210:211]
	v_or_b32_e32 v226, 16, v210
	v_lshl_add_u64 v[112:113], v[110:111], 0, v[112:113]
	v_ashrrev_i32_e32 v227, 31, v226
	global_load_dwordx4 v[190:193], v[112:113], off
	global_load_dwordx4 v[186:189], v[112:113], off offset:256
	v_lshlrev_b64 v[112:113], 11, v[226:227]
	v_or_b32_e32 v224, 32, v210
	v_lshl_add_u64 v[112:113], v[110:111], 0, v[112:113]
	v_ashrrev_i32_e32 v225, 31, v224
	global_load_dwordx4 v[182:185], v[112:113], off
	global_load_dwordx4 v[178:181], v[112:113], off offset:256
	v_lshlrev_b64 v[112:113], 11, v[224:225]
	v_or_b32_e32 v222, 48, v210
	v_lshl_add_u64 v[112:113], v[110:111], 0, v[112:113]
	v_ashrrev_i32_e32 v223, 31, v222
	global_load_dwordx4 v[174:177], v[112:113], off
	global_load_dwordx4 v[170:173], v[112:113], off offset:256
	v_lshlrev_b64 v[112:113], 11, v[222:223]
	v_add_u32_e32 v220, 0x80, v210
	v_lshl_add_u64 v[112:113], v[110:111], 0, v[112:113]
	v_ashrrev_i32_e32 v221, 31, v220
	global_load_dwordx4 v[166:169], v[112:113], off
	global_load_dwordx4 v[162:165], v[112:113], off offset:256
	v_lshlrev_b64 v[112:113], 11, v[220:221]
	v_add_u32_e32 v218, 0x90, v210
	v_lshl_add_u64 v[112:113], v[110:111], 0, v[112:113]
	v_ashrrev_i32_e32 v219, 31, v218
	global_load_dwordx4 v[158:161], v[112:113], off
	global_load_dwordx4 v[154:157], v[112:113], off offset:256
	v_lshlrev_b64 v[112:113], 11, v[218:219]
	v_add_u32_e32 v216, 0xa0, v210
	v_lshl_add_u64 v[112:113], v[110:111], 0, v[112:113]
	v_ashrrev_i32_e32 v217, 31, v216
	global_load_dwordx4 v[150:153], v[112:113], off
	global_load_dwordx4 v[146:149], v[112:113], off offset:256
	v_lshlrev_b64 v[112:113], 11, v[216:217]
	v_add_u32_e32 v214, 0xb0, v210
	v_lshl_add_u64 v[112:113], v[110:111], 0, v[112:113]
	v_ashrrev_i32_e32 v215, 31, v214
	global_load_dwordx4 v[142:145], v[112:113], off
	global_load_dwordx4 v[138:141], v[112:113], off offset:256
	v_lshlrev_b64 v[112:113], 11, v[214:215]
	v_lshl_add_u64 v[110:111], v[110:111], 0, v[112:113]
	global_load_dwordx4 v[118:121], v[110:111], off
	s_nop 0
	global_load_dwordx4 v[110:113], v[110:111], off offset:256
	v_cndmask_b32_e64 v228, 0, 1, s[74:75]
	v_cmp_ne_u32_e64 s[46:47], 1, v228
	v_lshlrev_b64 v[228:229], 10, v[210:211]
	v_lshl_add_u64 v[228:229], v[228:229], 0, v[212:213]
	s_andn2_b64 vcc, exec, s[74:75]
	s_waitcnt vmcnt(0)
	v_lshlrev_b32_e32 v248, 16, v190
	v_and_b32_e32 v249, 0xffff0000, v190
	v_lshlrev_b32_e32 v190, 16, v191
	v_and_b32_e32 v191, 0xffff0000, v191
	v_lshlrev_b32_e32 v250, 16, v192
	v_and_b32_e32 v251, 0xffff0000, v192
	v_lshlrev_b32_e32 v236, 16, v193
	v_and_b32_e32 v237, 0xffff0000, v193
	v_pk_add_f32 v[192:193], v[132:133], v[190:191]
	v_pk_add_f32 v[190:191], v[130:131], v[248:249]
	v_pk_add_f32 v[132:133], v[136:137], v[236:237]
	v_pk_add_f32 v[130:131], v[134:135], v[250:251]
	v_lshl_add_u64 v[136:137], v[228:229], 2, s[10:11]
	s_cbranch_vccnz .LBB0_279
	global_store_dwordx4 v[136:137], v[190:193], off nt
	global_store_dwordx4 v[136:137], v[130:133], off offset:16 nt

;     __device__ __forceinline__ void operator()(const f32x4 (&acc)[2][2][4][2], const Unit& u, int wr, int wc, int fr, int fq, PG8_LAS unsigned char* lds, int& rs_pm, int& rs_tog) const {
;     ...
;                     const u32x4 w_ = pre[slot][mm][bj];
;                     const f32x4 r0 = (f32x4){__uint_as_float(w_.x << 16), __uint_as_float(w_.x & 0xffff0000u), __uint_as_float(w_.y << 16), __uint_as_float(w_.y & 0xffff0000u)};
;                     const f32x4 r1 = (f32x4){__uint_as_float(w_.z << 16), __uint_as_float(w_.z & 0xffff0000u), __uint_as_float(w_.w << 16), __uint_as_float(w_.w & 0xffff0000u)};
;                     const f32x4 v0 = acc[ai][bj][m][0] + r0, v1 = acc[ai][bj][m][1] + r1;
;                     if (out32) { *(f32x4*)(out32 + off + bj * HALF) = v0; *(f32x4*)(out32 + off + bj * HALF + 4) = v1; }
.LBB0_282:
	v_lshlrev_b32_e32 v132, 16, v186
	v_and_b32_e32 v133, 0xffff0000, v186
	v_lshlrev_b32_e32 v186, 16, v187
	v_and_b32_e32 v187, 0xffff0000, v187
	v_lshlrev_b32_e32 v190, 16, v188
	v_and_b32_e32 v191, 0xffff0000, v188
	v_lshlrev_b32_e32 v188, 16, v189
	v_and_b32_e32 v189, 0xffff0000, v189
	v_pk_add_f32 v[128:129], v[128:129], v[186:187]
	v_pk_add_f32 v[126:127], v[126:127], v[132:133]
	v_pk_add_f32 v[124:125], v[124:125], v[188:189]
	s_and_b64 vcc, exec, s[46:47]
	v_pk_add_f32 v[122:123], v[122:123], v[190:191]
	s_cbranch_vccnz .LBB0_284
	global_store_dwordx4 v[136:137], v[126:129], off offset:512 nt
	global_store_dwordx4 v[136:137], v[122:125], off offset:528 nt

;     __device__ __forceinline__ void operator()(const f32x4 (&acc)[2][2][4][2], const Unit& u, int wr, int wc, int fr, int fq, PG8_LAS unsigned char* lds, int& rs_pm, int& rs_tog) const {
;     ...
;                     const u32x4 w_ = pre[slot][mm][bj];
;                     const f32x4 r0 = (f32x4){__uint_as_float(w_.x << 16), __uint_as_float(w_.x & 0xffff0000u), __uint_as_float(w_.y << 16), __uint_as_float(w_.y & 0xffff0000u)};
;                     const f32x4 r1 = (f32x4){__uint_as_float(w_.z << 16), __uint_as_float(w_.z & 0xffff0000u), __uint_as_float(w_.w << 16), __uint_as_float(w_.w & 0xffff0000u)};
;                     const f32x4 v0 = acc[ai][bj][m][0] + r0, v1 = acc[ai][bj][m][1] + r1;
;                     if (out32) { *(f32x4*)(out32 + off + bj * HALF) = v0; *(f32x4*)(out32 + off + bj * HALF + 4) = v1; }
.LBB0_290:
	s_waitcnt lgkmcnt(0)
	v_lshlrev_b64 v[122:123], 10, v[226:227]
	v_lshl_add_u64 v[122:123], v[122:123], 0, v[212:213]
	v_lshlrev_b32_e32 v124, 16, v182
	v_and_b32_e32 v125, 0xffff0000, v182
	v_lshlrev_b32_e32 v126, 16, v183
	v_and_b32_e32 v127, 0xffff0000, v183
	v_lshlrev_b32_e32 v128, 16, v184
	v_and_b32_e32 v129, 0xffff0000, v184
	v_lshlrev_b32_e32 v130, 16, v185
	v_and_b32_e32 v131, 0xffff0000, v185
	v_pk_add_f32 v[116:117], v[116:117], v[126:127]
	v_pk_add_f32 v[114:115], v[114:115], v[124:125]
	v_pk_add_f32 v[108:109], v[108:109], v[130:131]
	v_pk_add_f32 v[106:107], v[106:107], v[128:129]
	s_and_b64 vcc, exec, s[46:47]
	v_lshl_add_u64 v[124:125], v[122:123], 2, s[10:11]
	s_cbranch_vccnz .LBB0_292
	global_store_dwordx4 v[124:125], v[114:117], off nt
	global_store_dwordx4 v[124:125], v[106:109], off offset:16 nt

;     __device__ __forceinline__ void operator()(const f32x4 (&acc)[2][2][4][2], const Unit& u, int wr, int wc, int fr, int fq, PG8_LAS unsigned char* lds, int& rs_pm, int& rs_tog) const {
;     ...
;                     const u32x4 w_ = pre[slot][mm][bj];
;                     const f32x4 r0 = (f32x4){__uint_as_float(w_.x << 16), __uint_as_float(w_.x & 0xffff0000u), __uint_as_float(w_.y << 16), __uint_as_float(w_.y & 0xffff0000u)};
;                     const f32x4 r1 = (f32x4){__uint_as_float(w_.z << 16), __uint_as_float(w_.z & 0xffff0000u), __uint_as_float(w_.w << 16), __uint_as_float(w_.w & 0xffff0000u)};
;                     const f32x4 v0 = acc[ai][bj][m][0] + r0, v1 = acc[ai][bj][m][1] + r1;
;                     if (out32) { *(f32x4*)(out32 + off + bj * HALF) = v0; *(f32x4*)(out32 + off + bj * HALF + 4) = v1; }
.LBB0_295:
	v_lshlrev_b32_e32 v108, 16, v178
	v_and_b32_e32 v109, 0xffff0000, v178
	v_lshlrev_b32_e32 v114, 16, v179
	v_and_b32_e32 v115, 0xffff0000, v179
	v_lshlrev_b32_e32 v116, 16, v180
	v_and_b32_e32 v117, 0xffff0000, v180
	v_lshlrev_b32_e32 v126, 16, v181
	v_and_b32_e32 v127, 0xffff0000, v181
	v_pk_add_f32 v[104:105], v[104:105], v[114:115]
	v_pk_add_f32 v[102:103], v[102:103], v[108:109]
	v_pk_add_f32 v[100:101], v[100:101], v[126:127]
	s_and_b64 vcc, exec, s[46:47]
	v_pk_add_f32 v[98:99], v[98:99], v[116:117]
	s_cbranch_vccnz .LBB0_297
	global_store_dwordx4 v[124:125], v[102:105], off offset:512 nt
	global_store_dwordx4 v[124:125], v[98:101], off offset:528 nt

;     __device__ __forceinline__ void operator()(const f32x4 (&acc)[2][2][4][2], const Unit& u, int wr, int wc, int fr, int fq, PG8_LAS unsigned char* lds, int& rs_pm, int& rs_tog) const {
;     ...
;                     const u32x4 w_ = pre[slot][mm][bj];
;                     const f32x4 r0 = (f32x4){__uint_as_float(w_.x << 16), __uint_as_float(w_.x & 0xffff0000u), __uint_as_float(w_.y << 16), __uint_as_float(w_.y & 0xffff0000u)};
;                     const f32x4 r1 = (f32x4){__uint_as_float(w_.z << 16), __uint_as_float(w_.z & 0xffff0000u), __uint_as_float(w_.w << 16), __uint_as_float(w_.w & 0xffff0000u)};
;                     const f32x4 v0 = acc[ai][bj][m][0] + r0, v1 = acc[ai][bj][m][1] + r1;
;                     if (out32) { *(f32x4*)(out32 + off + bj * HALF) = v0; *(f32x4*)(out32 + off + bj * HALF + 4) = v1; }
.LBB0_303:
	s_waitcnt lgkmcnt(0)
	v_lshlrev_b64 v[98:99], 10, v[224:225]
	v_lshl_add_u64 v[98:99], v[98:99], 0, v[212:213]
	v_lshlrev_b32_e32 v100, 16, v174
	v_and_b32_e32 v101, 0xffff0000, v174
	v_lshlrev_b32_e32 v102, 16, v175
	v_and_b32_e32 v103, 0xffff0000, v175
	v_lshlrev_b32_e32 v104, 16, v176
	v_and_b32_e32 v105, 0xffff0000, v176
	v_lshlrev_b32_e32 v106, 16, v177
	v_and_b32_e32 v107, 0xffff0000, v177
	v_pk_add_f32 v[96:97], v[96:97], v[102:103]
	v_pk_add_f32 v[94:95], v[94:95], v[100:101]
	v_pk_add_f32 v[92:93], v[92:93], v[106:107]
	v_pk_add_f32 v[90:91], v[90:91], v[104:105]
	s_and_b64 vcc, exec, s[46:47]
	v_lshl_add_u64 v[100:101], v[98:99], 2, s[10:11]
	s_cbranch_vccnz .LBB0_305
	global_store_dwordx4 v[100:101], v[94:97], off nt
	global_store_dwordx4 v[100:101], v[90:93], off offset:16 nt

;     __device__ __forceinline__ void operator()(const f32x4 (&acc)[2][2][4][2], const Unit& u, int wr, int wc, int fr, int fq, PG8_LAS unsigned char* lds, int& rs_pm, int& rs_tog) const {
;     ...
;                     const u32x4 w_ = pre[slot][mm][bj];
;                     const f32x4 r0 = (f32x4){__uint_as_float(w_.x << 16), __uint_as_float(w_.x & 0xffff0000u), __uint_as_float(w_.y << 16), __uint_as_float(w_.y & 0xffff0000u)};
;                     const f32x4 r1 = (f32x4){__uint_as_float(w_.z << 16), __uint_as_float(w_.z & 0xffff0000u), __uint_as_float(w_.w << 16), __uint_as_float(w_.w & 0xffff0000u)};
;                     const f32x4 v0 = acc[ai][bj][m][0] + r0, v1 = acc[ai][bj][m][1] + r1;
;                     if (out32) { *(f32x4*)(out32 + off + bj * HALF) = v0; *(f32x4*)(out32 + off + bj * HALF + 4) = v1; }
.LBB0_308:
	v_lshlrev_b32_e32 v92, 16, v170
	v_and_b32_e32 v93, 0xffff0000, v170
	v_lshlrev_b32_e32 v94, 16, v171
	v_and_b32_e32 v95, 0xffff0000, v171
	v_lshlrev_b32_e32 v96, 16, v172
	v_and_b32_e32 v97, 0xffff0000, v172
	v_lshlrev_b32_e32 v102, 16, v173
	v_and_b32_e32 v103, 0xffff0000, v173
	v_pk_add_f32 v[88:89], v[88:89], v[94:95]
	v_pk_add_f32 v[86:87], v[86:87], v[92:93]
	v_pk_add_f32 v[84:85], v[84:85], v[102:103]
	s_and_b64 vcc, exec, s[46:47]
	v_pk_add_f32 v[82:83], v[82:83], v[96:97]
	s_cbranch_vccnz .LBB0_310
	global_store_dwordx4 v[100:101], v[86:89], off offset:512 nt
	global_store_dwordx4 v[100:101], v[82:85], off offset:528 nt

;     __device__ __forceinline__ void operator()(const f32x4 (&acc)[2][2][4][2], const Unit& u, int wr, int wc, int fr, int fq, PG8_LAS unsigned char* lds, int& rs_pm, int& rs_tog) const {
;     ...
;                     const u32x4 w_ = pre[slot][mm][bj];
;                     const f32x4 r0 = (f32x4){__uint_as_float(w_.x << 16), __uint_as_float(w_.x & 0xffff0000u), __uint_as_float(w_.y << 16), __uint_as_float(w_.y & 0xffff0000u)};
;                     const f32x4 r1 = (f32x4){__uint_as_float(w_.z << 16), __uint_as_float(w_.z & 0xffff0000u), __uint_as_float(w_.w << 16), __uint_as_float(w_.w & 0xffff0000u)};
;                     const f32x4 v0 = acc[ai][bj][m][0] + r0, v1 = acc[ai][bj][m][1] + r1;
;                     if (out32) { *(f32x4*)(out32 + off + bj * HALF) = v0; *(f32x4*)(out32 + off + bj * HALF + 4) = v1; }
.LBB0_316:
	s_waitcnt lgkmcnt(0)
	v_lshlrev_b64 v[82:83], 10, v[222:223]
	v_lshl_add_u64 v[82:83], v[82:83], 0, v[212:213]
	v_lshlrev_b32_e32 v84, 16, v166
	v_and_b32_e32 v85, 0xffff0000, v166
	v_lshlrev_b32_e32 v86, 16, v167
	v_and_b32_e32 v87, 0xffff0000, v167
	v_lshlrev_b32_e32 v88, 16, v168
	v_and_b32_e32 v89, 0xffff0000, v168
	v_lshlrev_b32_e32 v90, 16, v169
	v_and_b32_e32 v91, 0xffff0000, v169
	v_pk_add_f32 v[80:81], v[80:81], v[86:87]
	v_pk_add_f32 v[78:79], v[78:79], v[84:85]
	v_pk_add_f32 v[76:77], v[76:77], v[90:91]
	v_pk_add_f32 v[74:75], v[74:75], v[88:89]
	s_and_b64 vcc, exec, s[46:47]
	v_lshl_add_u64 v[84:85], v[82:83], 2, s[10:11]
	s_cbranch_vccnz .LBB0_318
	global_store_dwordx4 v[84:85], v[78:81], off nt
	global_store_dwordx4 v[84:85], v[74:77], off offset:16 nt

;     __device__ __forceinline__ void operator()(const f32x4 (&acc)[2][2][4][2], const Unit& u, int wr, int wc, int fr, int fq, PG8_LAS unsigned char* lds, int& rs_pm, int& rs_tog) const {
;     ...
;                     const u32x4 w_ = pre[slot][mm][bj];
;                     const f32x4 r0 = (f32x4){__uint_as_float(w_.x << 16), __uint_as_float(w_.x & 0xffff0000u), __uint_as_float(w_.y << 16), __uint_as_float(w_.y & 0xffff0000u)};
;                     const f32x4 r1 = (f32x4){__uint_as_float(w_.z << 16), __uint_as_float(w_.z & 0xffff0000u), __uint_as_float(w_.w << 16), __uint_as_float(w_.w & 0xffff0000u)};
;                     const f32x4 v0 = acc[ai][bj][m][0] + r0, v1 = acc[ai][bj][m][1] + r1;
;                     if (out32) { *(f32x4*)(out32 + off + bj * HALF) = v0; *(f32x4*)(out32 + off + bj * HALF + 4) = v1; }
.LBB0_321:
	v_lshlrev_b32_e32 v76, 16, v162
	v_and_b32_e32 v77, 0xffff0000, v162
	v_lshlrev_b32_e32 v78, 16, v163
	v_and_b32_e32 v79, 0xffff0000, v163
	v_lshlrev_b32_e32 v80, 16, v164
	v_and_b32_e32 v81, 0xffff0000, v164
	v_lshlrev_b32_e32 v86, 16, v165
	v_and_b32_e32 v87, 0xffff0000, v165
	v_pk_add_f32 v[72:73], v[72:73], v[78:79]
	v_pk_add_f32 v[70:71], v[70:71], v[76:77]
	v_pk_add_f32 v[68:69], v[68:69], v[86:87]
	s_and_b64 vcc, exec, s[46:47]
	v_pk_add_f32 v[66:67], v[66:67], v[80:81]
	s_cbranch_vccnz .LBB0_323
	global_store_dwordx4 v[84:85], v[70:73], off offset:512 nt
	global_store_dwordx4 v[84:85], v[66:69], off offset:528 nt

;     __device__ __forceinline__ void operator()(const f32x4 (&acc)[2][2][4][2], const Unit& u, int wr, int wc, int fr, int fq, PG8_LAS unsigned char* lds, int& rs_pm, int& rs_tog) const {
;     ...
;                     const u32x4 w_ = pre[slot][mm][bj];
;                     const f32x4 r0 = (f32x4){__uint_as_float(w_.x << 16), __uint_as_float(w_.x & 0xffff0000u), __uint_as_float(w_.y << 16), __uint_as_float(w_.y & 0xffff0000u)};
;                     const f32x4 r1 = (f32x4){__uint_as_float(w_.z << 16), __uint_as_float(w_.z & 0xffff0000u), __uint_as_float(w_.w << 16), __uint_as_float(w_.w & 0xffff0000u)};
;                     const f32x4 v0 = acc[ai][bj][m][0] + r0, v1 = acc[ai][bj][m][1] + r1;
;                     if (out32) { *(f32x4*)(out32 + off + bj * HALF) = v0; *(f32x4*)(out32 + off + bj * HALF + 4) = v1; }
.LBB0_329:
	s_waitcnt lgkmcnt(0)
	v_lshlrev_b64 v[66:67], 10, v[220:221]
	v_lshl_add_u64 v[66:67], v[66:67], 0, v[212:213]
	v_lshlrev_b32_e32 v68, 16, v158
	v_and_b32_e32 v69, 0xffff0000, v158
	v_lshlrev_b32_e32 v70, 16, v159
	v_and_b32_e32 v71, 0xffff0000, v159
	v_lshlrev_b32_e32 v72, 16, v160
	v_and_b32_e32 v73, 0xffff0000, v160
	v_lshlrev_b32_e32 v74, 16, v161
	v_and_b32_e32 v75, 0xffff0000, v161
	v_pk_add_f32 v[64:65], v[64:65], v[70:71]
	v_pk_add_f32 v[62:63], v[62:63], v[68:69]
	v_pk_add_f32 v[60:61], v[60:61], v[74:75]
	v_pk_add_f32 v[58:59], v[58:59], v[72:73]
	s_and_b64 vcc, exec, s[46:47]
	v_lshl_add_u64 v[68:69], v[66:67], 2, s[10:11]
	s_cbranch_vccnz .LBB0_331
	global_store_dwordx4 v[68:69], v[62:65], off nt
	global_store_dwordx4 v[68:69], v[58:61], off offset:16 nt

;     __device__ __forceinline__ void operator()(const f32x4 (&acc)[2][2][4][2], const Unit& u, int wr, int wc, int fr, int fq, PG8_LAS unsigned char* lds, int& rs_pm, int& rs_tog) const {
;     ...
;                     const u32x4 w_ = pre[slot][mm][bj];
;                     const f32x4 r0 = (f32x4){__uint_as_float(w_.x << 16), __uint_as_float(w_.x & 0xffff0000u), __uint_as_float(w_.y << 16), __uint_as_float(w_.y & 0xffff0000u)};
;                     const f32x4 r1 = (f32x4){__uint_as_float(w_.z << 16), __uint_as_float(w_.z & 0xffff0000u), __uint_as_float(w_.w << 16), __uint_as_float(w_.w & 0xffff0000u)};
;                     const f32x4 v0 = acc[ai][bj][m][0] + r0, v1 = acc[ai][bj][m][1] + r1;
;                     if (out32) { *(f32x4*)(out32 + off + bj * HALF) = v0; *(f32x4*)(out32 + off + bj * HALF + 4) = v1; }
.LBB0_334:
	v_lshlrev_b32_e32 v60, 16, v154
	v_and_b32_e32 v61, 0xffff0000, v154
	v_lshlrev_b32_e32 v62, 16, v155
	v_and_b32_e32 v63, 0xffff0000, v155
	v_lshlrev_b32_e32 v64, 16, v156
	v_and_b32_e32 v65, 0xffff0000, v156
	v_lshlrev_b32_e32 v70, 16, v157
	v_and_b32_e32 v71, 0xffff0000, v157
	v_pk_add_f32 v[56:57], v[56:57], v[62:63]
	v_pk_add_f32 v[54:55], v[54:55], v[60:61]
	v_pk_add_f32 v[52:53], v[52:53], v[70:71]
	s_and_b64 vcc, exec, s[46:47]
	v_pk_add_f32 v[50:51], v[50:51], v[64:65]
	s_cbranch_vccnz .LBB0_336
	global_store_dwordx4 v[68:69], v[54:57], off offset:512 nt
	global_store_dwordx4 v[68:69], v[50:53], off offset:528 nt

;     __device__ __forceinline__ void operator()(const f32x4 (&acc)[2][2][4][2], const Unit& u, int wr, int wc, int fr, int fq, PG8_LAS unsigned char* lds, int& rs_pm, int& rs_tog) const {
;     ...
;                     const u32x4 w_ = pre[slot][mm][bj];
;                     const f32x4 r0 = (f32x4){__uint_as_float(w_.x << 16), __uint_as_float(w_.x & 0xffff0000u), __uint_as_float(w_.y << 16), __uint_as_float(w_.y & 0xffff0000u)};
;                     const f32x4 r1 = (f32x4){__uint_as_float(w_.z << 16), __uint_as_float(w_.z & 0xffff0000u), __uint_as_float(w_.w << 16), __uint_as_float(w_.w & 0xffff0000u)};
;                     const f32x4 v0 = acc[ai][bj][m][0] + r0, v1 = acc[ai][bj][m][1] + r1;
;                     if (out32) { *(f32x4*)(out32 + off + bj * HALF) = v0; *(f32x4*)(out32 + off + bj * HALF + 4) = v1; }
.LBB0_342:
	s_waitcnt lgkmcnt(0)
	v_lshlrev_b64 v[50:51], 10, v[218:219]
	v_lshl_add_u64 v[50:51], v[50:51], 0, v[212:213]
	v_lshlrev_b32_e32 v52, 16, v150
	v_and_b32_e32 v53, 0xffff0000, v150
	v_lshlrev_b32_e32 v54, 16, v151
	v_and_b32_e32 v55, 0xffff0000, v151
	v_lshlrev_b32_e32 v56, 16, v152
	v_and_b32_e32 v57, 0xffff0000, v152
	v_lshlrev_b32_e32 v58, 16, v153
	v_and_b32_e32 v59, 0xffff0000, v153
	v_pk_add_f32 v[48:49], v[48:49], v[54:55]
	v_pk_add_f32 v[46:47], v[46:47], v[52:53]
	v_pk_add_f32 v[44:45], v[44:45], v[58:59]
	v_pk_add_f32 v[42:43], v[42:43], v[56:57]
	s_and_b64 vcc, exec, s[46:47]
	v_lshl_add_u64 v[52:53], v[50:51], 2, s[10:11]
	s_cbranch_vccnz .LBB0_344
	global_store_dwordx4 v[52:53], v[46:49], off nt
	global_store_dwordx4 v[52:53], v[42:45], off offset:16 nt

;     __device__ __forceinline__ void operator()(const f32x4 (&acc)[2][2][4][2], const Unit& u, int wr, int wc, int fr, int fq, PG8_LAS unsigned char* lds, int& rs_pm, int& rs_tog) const {
;     ...
;                     const u32x4 w_ = pre[slot][mm][bj];
;                     const f32x4 r0 = (f32x4){__uint_as_float(w_.x << 16), __uint_as_float(w_.x & 0xffff0000u), __uint_as_float(w_.y << 16), __uint_as_float(w_.y & 0xffff0000u)};
;                     const f32x4 r1 = (f32x4){__uint_as_float(w_.z << 16), __uint_as_float(w_.z & 0xffff0000u), __uint_as_float(w_.w << 16), __uint_as_float(w_.w & 0xffff0000u)};
;                     const f32x4 v0 = acc[ai][bj][m][0] + r0, v1 = acc[ai][bj][m][1] + r1;
;                     if (out32) { *(f32x4*)(out32 + off + bj * HALF) = v0; *(f32x4*)(out32 + off + bj * HALF + 4) = v1; }
.LBB0_347:
	v_lshlrev_b32_e32 v44, 16, v146
	v_and_b32_e32 v45, 0xffff0000, v146
	v_lshlrev_b32_e32 v46, 16, v147
	v_and_b32_e32 v47, 0xffff0000, v147
	v_lshlrev_b32_e32 v48, 16, v148
	v_and_b32_e32 v49, 0xffff0000, v148
	v_lshlrev_b32_e32 v54, 16, v149
	v_and_b32_e32 v55, 0xffff0000, v149
	v_pk_add_f32 v[40:41], v[40:41], v[46:47]
	v_pk_add_f32 v[38:39], v[38:39], v[44:45]
	v_pk_add_f32 v[36:37], v[36:37], v[54:55]
	s_and_b64 vcc, exec, s[46:47]
	v_pk_add_f32 v[34:35], v[34:35], v[48:49]
	s_cbranch_vccnz .LBB0_349
	global_store_dwordx4 v[52:53], v[38:41], off offset:512 nt
	global_store_dwordx4 v[52:53], v[34:37], off offset:528 nt

;     __device__ __forceinline__ void operator()(const f32x4 (&acc)[2][2][4][2], const Unit& u, int wr, int wc, int fr, int fq, PG8_LAS unsigned char* lds, int& rs_pm, int& rs_tog) const {
;     ...
;                     const u32x4 w_ = pre[slot][mm][bj];
;                     const f32x4 r0 = (f32x4){__uint_as_float(w_.x << 16), __uint_as_float(w_.x & 0xffff0000u), __uint_as_float(w_.y << 16), __uint_as_float(w_.y & 0xffff0000u)};
;                     const f32x4 r1 = (f32x4){__uint_as_float(w_.z << 16), __uint_as_float(w_.z & 0xffff0000u), __uint_as_float(w_.w << 16), __uint_as_float(w_.w & 0xffff0000u)};
;                     const f32x4 v0 = acc[ai][bj][m][0] + r0, v1 = acc[ai][bj][m][1] + r1;
;                     if (out32) { *(f32x4*)(out32 + off + bj * HALF) = v0; *(f32x4*)(out32 + off + bj * HALF + 4) = v1; }
.LBB0_355:
	s_waitcnt lgkmcnt(0)
	v_lshlrev_b64 v[34:35], 10, v[216:217]
	v_lshl_add_u64 v[34:35], v[34:35], 0, v[212:213]
	v_lshlrev_b32_e32 v36, 16, v142
	v_and_b32_e32 v37, 0xffff0000, v142
	v_lshlrev_b32_e32 v38, 16, v143
	v_and_b32_e32 v39, 0xffff0000, v143
	v_lshlrev_b32_e32 v40, 16, v144
	v_and_b32_e32 v41, 0xffff0000, v144
	v_lshlrev_b32_e32 v42, 16, v145
	v_and_b32_e32 v43, 0xffff0000, v145
	v_pk_add_f32 v[32:33], v[32:33], v[38:39]
	v_pk_add_f32 v[30:31], v[30:31], v[36:37]
	v_pk_add_f32 v[28:29], v[28:29], v[42:43]
	v_pk_add_f32 v[26:27], v[26:27], v[40:41]
	s_and_b64 vcc, exec, s[46:47]
	v_lshl_add_u64 v[36:37], v[34:35], 2, s[10:11]
	s_cbranch_vccnz .LBB0_357
	global_store_dwordx4 v[36:37], v[30:33], off nt
	global_store_dwordx4 v[36:37], v[26:29], off offset:16 nt

;     __device__ __forceinline__ void operator()(const f32x4 (&acc)[2][2][4][2], const Unit& u, int wr, int wc, int fr, int fq, PG8_LAS unsigned char* lds, int& rs_pm, int& rs_tog) const {
;     ...
;                     const u32x4 w_ = pre[slot][mm][bj];
;                     const f32x4 r0 = (f32x4){__uint_as_float(w_.x << 16), __uint_as_float(w_.x & 0xffff0000u), __uint_as_float(w_.y << 16), __uint_as_float(w_.y & 0xffff0000u)};
;                     const f32x4 r1 = (f32x4){__uint_as_float(w_.z << 16), __uint_as_float(w_.z & 0xffff0000u), __uint_as_float(w_.w << 16), __uint_as_float(w_.w & 0xffff0000u)};
;                     const f32x4 v0 = acc[ai][bj][m][0] + r0, v1 = acc[ai][bj][m][1] + r1;
;                     if (out32) { *(f32x4*)(out32 + off + bj * HALF) = v0; *(f32x4*)(out32 + off + bj * HALF + 4) = v1; }
.LBB0_360:
	v_lshlrev_b32_e32 v28, 16, v138
	v_and_b32_e32 v29, 0xffff0000, v138
	v_lshlrev_b32_e32 v30, 16, v139
	v_and_b32_e32 v31, 0xffff0000, v139
	v_lshlrev_b32_e32 v32, 16, v140
	v_and_b32_e32 v33, 0xffff0000, v140
	v_lshlrev_b32_e32 v38, 16, v141
	v_and_b32_e32 v39, 0xffff0000, v141
	v_pk_add_f32 v[24:25], v[24:25], v[30:31]
	v_pk_add_f32 v[22:23], v[22:23], v[28:29]
	v_pk_add_f32 v[20:21], v[20:21], v[38:39]
	s_and_b64 vcc, exec, s[46:47]
	v_pk_add_f32 v[18:19], v[18:19], v[32:33]
	s_cbranch_vccnz .LBB0_362
	global_store_dwordx4 v[36:37], v[22:25], off offset:512 nt
	global_store_dwordx4 v[36:37], v[18:21], off offset:528 nt

;     __device__ __forceinline__ void operator()(const f32x4 (&acc)[2][2][4][2], const Unit& u, int wr, int wc, int fr, int fq, PG8_LAS unsigned char* lds, int& rs_pm, int& rs_tog) const {
;     ...
;                     const u32x4 w_ = pre[slot][mm][bj];
;                     const f32x4 r0 = (f32x4){__uint_as_float(w_.x << 16), __uint_as_float(w_.x & 0xffff0000u), __uint_as_float(w_.y << 16), __uint_as_float(w_.y & 0xffff0000u)};
;                     const f32x4 r1 = (f32x4){__uint_as_float(w_.z << 16), __uint_as_float(w_.z & 0xffff0000u), __uint_as_float(w_.w << 16), __uint_as_float(w_.w & 0xffff0000u)};
;                     const f32x4 v0 = acc[ai][bj][m][0] + r0, v1 = acc[ai][bj][m][1] + r1;
;                     if (out32) { *(f32x4*)(out32 + off + bj * HALF) = v0; *(f32x4*)(out32 + off + bj * HALF + 4) = v1; }
.LBB0_368:
	s_waitcnt lgkmcnt(0)
	v_lshlrev_b64 v[18:19], 10, v[214:215]
	v_lshl_add_u64 v[18:19], v[18:19], 0, v[212:213]
	v_lshlrev_b32_e32 v20, 16, v118
	v_and_b32_e32 v21, 0xffff0000, v118
	v_lshlrev_b32_e32 v22, 16, v119
	v_and_b32_e32 v23, 0xffff0000, v119
	v_lshlrev_b32_e32 v24, 16, v120
	v_and_b32_e32 v25, 0xffff0000, v120
	v_lshlrev_b32_e32 v26, 16, v121
	v_and_b32_e32 v27, 0xffff0000, v121
	v_pk_add_f32 v[16:17], v[16:17], v[22:23]
	v_pk_add_f32 v[14:15], v[14:15], v[20:21]
	v_pk_add_f32 v[12:13], v[12:13], v[26:27]
	v_pk_add_f32 v[10:11], v[10:11], v[24:25]
	s_and_b64 vcc, exec, s[46:47]
	v_lshl_add_u64 v[20:21], v[18:19], 2, s[10:11]
	s_cbranch_vccnz .LBB0_370
	global_store_dwordx4 v[20:21], v[14:17], off nt
	global_store_dwordx4 v[20:21], v[10:13], off offset:16 nt

;     __device__ __forceinline__ void operator()(const f32x4 (&acc)[2][2][4][2], const Unit& u, int wr, int wc, int fr, int fq, PG8_LAS unsigned char* lds, int& rs_pm, int& rs_tog) const {
;     ...
;                     const u32x4 w_ = pre[slot][mm][bj];
;                     const f32x4 r0 = (f32x4){__uint_as_float(w_.x << 16), __uint_as_float(w_.x & 0xffff0000u), __uint_as_float(w_.y << 16), __uint_as_float(w_.y & 0xffff0000u)};
;                     const f32x4 r1 = (f32x4){__uint_as_float(w_.z << 16), __uint_as_float(w_.z & 0xffff0000u), __uint_as_float(w_.w << 16), __uint_as_float(w_.w & 0xffff0000u)};
;                     const f32x4 v0 = acc[ai][bj][m][0] + r0, v1 = acc[ai][bj][m][1] + r1;
;                     if (out32) { *(f32x4*)(out32 + off + bj * HALF) = v0; *(f32x4*)(out32 + off + bj * HALF + 4) = v1; }
.LBB0_373:
	v_lshlrev_b32_e32 v12, 16, v110
	v_and_b32_e32 v13, 0xffff0000, v110
	v_lshlrev_b32_e32 v14, 16, v111
	v_and_b32_e32 v15, 0xffff0000, v111
	v_lshlrev_b32_e32 v16, 16, v112
	v_and_b32_e32 v17, 0xffff0000, v112
	v_lshlrev_b32_e32 v22, 16, v113
	v_and_b32_e32 v23, 0xffff0000, v113
	v_pk_add_f32 v[8:9], v[8:9], v[14:15]
	v_pk_add_f32 v[6:7], v[6:7], v[12:13]
	v_pk_add_f32 v[4:5], v[4:5], v[22:23]
	s_and_b64 vcc, exec, s[46:47]
	v_pk_add_f32 v[2:3], v[2:3], v[16:17]
	s_cbranch_vccnz .LBB0_375
	global_store_dwordx4 v[20:21], v[6:9], off offset:512 nt
	global_store_dwordx4 v[20:21], v[2:5], off offset:528 nt
